# attention: waves 4-7 take the per-tile barrier and next-tile LDS commit after QK instead of after PV (K 2 slots, V 3 slots) so SIMD partner waves run MFMA and softmax out of phase
# baseline (speedup 1.0000x reference)
; __device__ __forceinline__ void unpack8(const u32x4 w, float (&f)[8]) { f[0] = bflo(w.x); f[1] = bfhi(w.x); f[2] = bflo(w.y); f[3] = bfhi(w.y); f[4] = bflo(w.z); f[5] = bfhi(w.z); f[6] = bflo(w.w); f[7] = bfhi(w.w); }
; __device__ __forceinline__ u32x4 pack8(const float (&f)[8]) { u32x4 w; w.x = pk_bf16(f[0], f[1]); w.y = pk_bf16(f[2], f[3]); w.z = pk_bf16(f[4], f[5]); w.w = pk_bf16(f[6], f[7]); return w; }
; __device__ __forceinline__ void attn_phase(LAS unsigned char* lds, const bf16* Q, const bf16* KV, const bf16* KPE, const float* rope, bf16* mix, int bid, int G, int tid) {
;     ...
;     for (int round = 0; round * G < AT_UNITS; ++round) {
;         int idx;
;         if (G == 256) { const int i2 = bid >> 1, od = bid & 1;
;             idx = (round == 0) ? bid : (round == 1 ? 256 + (od ? 127 - i2 : 255 - i2) : 512 + (od ? 255 - i2 : 127 - i2)); }
;         else idx = (round & 1) ? (round * G + (G - 1 - bid)) : (round * G + bid);
;         if (idx >= AT_UNITS) continue;
;         int tid_r = tid; asm volatile("" : "+v"(tid_r));
;         const int lane = tid_r & 63, l32 = lane & 31, hh = lane >> 5;
;         const int sr16 = tid_r >> 4, sc16 = tid_r & 15, sr8 = tid_r >> 3, sc8 = tid_r & 7;
;         const int qb = 15 - idx / 48, bh = idx % 48, b = bh / 12, h = bh - b * 12;
;         const int q0 = qb * 256, mrow0 = b * SEQ, ntiles = (qb + 1) * 4;
;         const int qrow = mrow0 + q0 + wid * 32 + l32;
;         bf16x8 qf[12];
;         { const bf16* qp = Q + (size_t)qrow * 2304 + h * 192 + hh * 8; const float* rp = rope + (size_t)qrow * 64;
; #pragma unroll
;           for (int ks = 0; ks < 8; ++ks) { float f[8]; unpack8(*(const u32x4*)(qp + ks * 16), f);
; #pragma unroll
;               for (int e = 0; e < 8; ++e) f[e] *= qs;
;               qf[ks] = __builtin_bit_cast(bf16x8, pack8(f)); if (ks & 1) asm volatile("" ::: "memory"); }
.LBB0_249:
	s_cmpk_gt_i32 s4, 0x2ff
	s_cbranch_scc1 .LBB0_240
	s_mul_hi_i32 s0, s4, 0xd5555555
	s_lshr_b32 s1, s0, 31
	s_ashr_i32 s0, s0, 3
	s_add_i32 s1, s0, s1
	s_mul_hi_i32 s0, s4, 0x2aaaaaab
	s_lshr_b32 s5, s0, 31
	s_lshr_b32 s0, s0, 3
	s_add_i32 s0, s0, s5
	s_mul_i32 s0, s0, 48
	s_sub_i32 s4, s4, s0
	s_mul_i32 s0, s4, 43
	s_sext_i32_i16 s5, s0
	s_lshr_b32 s5, s5, 9
	s_bfe_u32 s0, s0, 0x1000f
	s_add_i32 s5, s5, s0
	s_sext_i32_i16 s0, s5
	s_mul_i32 s7, s0, -12
	s_add_i32 s7, s7, s4
	s_lshl_b32 s4, s1, 8
	s_waitcnt vmcnt(0)
	v_mov_b32_e32 v23, v186
	s_lshl_b32 s34, s0, 12
	s_add_i32 s8, s2, s4
	s_add_i32 s4, s34, s8
	v_and_b32_e32 v22, 31, v23
	v_or_b32_e32 v174, s4, v22
	v_readlane_b32 s4, v255, 1
	v_readlane_b32 s5, v255, 2
	v_bfe_u32 v24, v23, 5, 1
	v_lshlrev_b32_e32 v96, 4, v24
	s_waitcnt lgkmcnt(0)
	v_mov_b64_e32 v[0:1], s[4:5]
	s_movk_i32 s4, 0x1200
	v_mad_i64_i32 v[0:1], s[4:5], v174, s4, v[0:1]
	s_mul_i32 s4, s7, 0xc0
	s_ashr_i32 s5, s4, 31
	v_lshl_add_u64 v[0:1], s[4:5], 1, v[0:1]
	v_lshl_add_u64 v[4:5], v[0:1], 0, v[96:97]
	global_load_dwordx4 v[6:9], v[4:5], off
	global_load_dwordx4 v[10:13], v[4:5], off offset:32
	global_load_dwordx4 v[14:17], v[4:5], off offset:64
	global_load_dwordx4 v[26:29], v[4:5], off offset:96
	global_load_dwordx4 v[30:33], v[4:5], off offset:128
	global_load_dwordx4 v[34:37], v[4:5], off offset:160
	s_mov_b32 s28, 0x3dd53b94
	v_ashrrev_i32_e32 v175, 31, v174
	v_lshlrev_b64 v[18:19], 8, v[174:175]
	global_load_dwordx4 v[38:41], v[4:5], off offset:192
	global_load_dwordx4 v[0:3], v[4:5], off offset:224
	s_lshl_b32 s9, s1, 2
	s_add_i32 s9, s9, 64
	s_ashr_i32 s35, s34, 31
	s_mul_i32 s17, s0, 0x1800000
	v_readlane_b32 s0, v255, 5
	s_mul_hi_i32 s19, s34, 0x1800
	v_readlane_b32 s1, v255, 6
	s_add_u32 s4, s0, s17
	s_addc_u32 s5, s1, s19
	s_lshl_b32 s0, s7, 8
	s_ashr_i32 s1, s0, 31
	v_ashrrev_i32_e32 v25, 4, v23
	s_lshl_b64 s[0:1], s[0:1], 1
	s_movk_i32 s11, 0x1800
	s_add_u32 s14, s4, s0
	s_addc_u32 s15, s5, s1
	s_lshl_b64 s[4:5], s[34:35], 7
	v_readlane_b32 s30, v255, 3
	v_readlane_b32 s31, v255, 4
	s_add_u32 s30, s30, s4
	s_addc_u32 s31, s31, s5
	v_lshlrev_b32_e32 v189, 2, v24
	v_mul_u32_u24_e32 v203, 0x190, v22
	v_or_b32_e32 v206, s8, v22
	v_mov_b32_e32 v184, 0xf149f2ca
	v_mov_b32_e32 v207, 0
	s_waitcnt vmcnt(0) lgkmcnt(0)
	v_lshlrev_b32_e32 v42, 16, v8
	v_and_b32_e32 v43, 0xffff0000, v8
	v_lshlrev_b32_e32 v8, 16, v9
	v_and_b32_e32 v9, 0xffff0000, v9
	v_lshlrev_b32_e32 v44, 16, v10
	v_and_b32_e32 v45, 0xffff0000, v10
	v_lshlrev_b32_e32 v10, 16, v11
	v_and_b32_e32 v11, 0xffff0000, v11
	v_pk_mul_f32 v[8:9], v[8:9], s[28:29] op_sel_hi:[1,0]
	v_lshlrev_b32_e32 v48, 16, v14
	v_and_b32_e32 v49, 0xffff0000, v14
	v_lshlrev_b32_e32 v14, 16, v15
	v_and_b32_e32 v15, 0xffff0000, v15
	v_pk_mul_f32 v[10:11], v[10:11], s[28:29] op_sel_hi:[1,0]
	v_lshlrev_b32_e32 v50, 16, v16
	v_and_b32_e32 v51, 0xffff0000, v16
	v_cvt_pk_bf16_f32 v101, v8, v9
	v_pk_mul_f32 v[8:9], v[14:15], s[28:29] op_sel_hi:[1,0]
	v_lshlrev_b32_e32 v20, 16, v6
	v_and_b32_e32 v21, 0xffff0000, v6
	v_lshlrev_b32_e32 v46, 16, v12
	v_and_b32_e32 v47, 0xffff0000, v12
	v_lshlrev_b32_e32 v12, 16, v13
	v_and_b32_e32 v13, 0xffff0000, v13
	v_cvt_pk_bf16_f32 v103, v10, v11
	v_pk_mul_f32 v[10:11], v[50:51], s[28:29] op_sel_hi:[1,0]
	v_cvt_pk_bf16_f32 v107, v8, v9
	v_lshlrev_b32_e32 v8, 16, v27
	v_and_b32_e32 v9, 0xffff0000, v27
	v_pk_mul_f32 v[20:21], v[20:21], s[28:29] op_sel_hi:[1,0]
	v_pk_mul_f32 v[12:13], v[12:13], s[28:29] op_sel_hi:[1,0]
	v_lshlrev_b32_e32 v16, 16, v17
	v_and_b32_e32 v17, 0xffff0000, v17
	v_lshlrev_b32_e32 v52, 16, v26
	v_and_b32_e32 v53, 0xffff0000, v26
	v_cvt_pk_bf16_f32 v108, v10, v11
	v_pk_mul_f32 v[26:27], v[8:9], s[28:29] op_sel_hi:[1,0]
	v_lshl_add_u64 v[8:9], s[56:57], 0, v[18:19]
	v_lshlrev_b32_e32 v10, 6, v24
	v_mov_b32_e32 v11, v97
	v_cvt_pk_bf16_f32 v98, v20, v21
	v_cvt_pk_bf16_f32 v105, v12, v13
	v_pk_mul_f32 v[12:13], v[16:17], s[28:29] op_sel_hi:[1,0]
	v_lshl_add_u64 v[20:21], v[8:9], 0, v[10:11]
	v_cvt_pk_bf16_f32 v109, v12, v13
	global_load_dwordx4 v[16:19], v[20:21], off
	global_load_dwordx4 v[8:11], v[4:5], off offset:256
	global_load_dwordx4 v[12:15], v[4:5], off offset:320
	v_lshlrev_b32_e32 v6, 16, v7
	v_and_b32_e32 v7, 0xffff0000, v7
	v_pk_mul_f32 v[6:7], v[6:7], s[28:29] op_sel_hi:[1,0]
	v_pk_mul_f32 v[42:43], v[42:43], s[28:29] op_sel_hi:[1,0]
	v_cvt_pk_bf16_f32 v99, v6, v7
	v_pk_mul_f32 v[6:7], v[48:49], s[28:29] op_sel_hi:[1,0]
	v_cvt_pk_bf16_f32 v100, v42, v43
	v_cvt_pk_bf16_f32 v106, v6, v7
	v_pk_mul_f32 v[6:7], v[52:53], s[28:29] op_sel_hi:[1,0]
	v_lshlrev_b32_e32 v42, 16, v28
	v_and_b32_e32 v43, 0xffff0000, v28
	v_cvt_pk_bf16_f32 v111, v26, v27
	v_lshlrev_b32_e32 v26, 16, v31
	v_and_b32_e32 v27, 0xffff0000, v31
	v_pk_mul_f32 v[42:43], v[42:43], s[28:29] op_sel_hi:[1,0]
	v_lshlrev_b32_e32 v28, 16, v29
	v_and_b32_e32 v29, 0xffff0000, v29
	v_cvt_pk_bf16_f32 v110, v6, v7
	v_lshlrev_b32_e32 v6, 16, v30
	v_and_b32_e32 v7, 0xffff0000, v30
	v_pk_mul_f32 v[30:31], v[26:27], s[28:29] op_sel_hi:[1,0]
	v_lshlrev_b32_e32 v26, 16, v32
	v_and_b32_e32 v27, 0xffff0000, v32
	v_pk_mul_f32 v[28:29], v[28:29], s[28:29] op_sel_hi:[1,0]
	v_cvt_pk_bf16_f32 v112, v42, v43
	v_pk_mul_f32 v[6:7], v[6:7], s[28:29] op_sel_hi:[1,0]
	v_pk_mul_f32 v[42:43], v[26:27], s[28:29] op_sel_hi:[1,0]
	v_lshlrev_b32_e32 v26, 16, v33
	v_and_b32_e32 v27, 0xffff0000, v33
	v_cvt_pk_bf16_f32 v113, v28, v29
	v_pk_mul_f32 v[32:33], v[26:27], s[28:29] op_sel_hi:[1,0]
	global_load_dwordx4 v[26:29], v[20:21], off offset:16
	v_cvt_pk_bf16_f32 v114, v6, v7
	v_cvt_pk_bf16_f32 v115, v30, v31
	v_lshlrev_b32_e32 v6, 16, v34
	v_and_b32_e32 v7, 0xffff0000, v34
; __device__ __forceinline__ void unpack8(const u32x4 w, float (&f)[8]) { f[0] = bflo(w.x); f[1] = bfhi(w.x); f[2] = bflo(w.y); f[3] = bfhi(w.y); f[4] = bflo(w.z); f[5] = bfhi(w.z); f[6] = bflo(w.w); f[7] = bfhi(w.w); }
; __device__ __forceinline__ u32x4 pack8(const float (&f)[8]) { u32x4 w; w.x = pk_bf16(f[0], f[1]); w.y = pk_bf16(f[2], f[3]); w.z = pk_bf16(f[4], f[5]); w.w = pk_bf16(f[6], f[7]); return w; }
; __device__ __forceinline__ void attn_phase(LAS unsigned char* lds, const bf16* Q, const bf16* KV, const bf16* KPE, const float* rope, bf16* mix, int bid, int G, int tid) {
;     ...
;         { const bf16* qp = Q + (size_t)qrow * 2304 + h * 192 + hh * 8; const float* rp = rope + (size_t)qrow * 64;
; #pragma unroll
;           for (int ks = 0; ks < 8; ++ks) { float f[8]; unpack8(*(const u32x4*)(qp + ks * 16), f);
; #pragma unroll
;               for (int e = 0; e < 8; ++e) f[e] *= qs;
;               qf[ks] = __builtin_bit_cast(bf16x8, pack8(f)); if (ks & 1) asm volatile("" ::: "memory"); }
; #pragma unroll
;           for (int ks = 8; ks < 10; ++ks) { float f1[8], f2[8], o1[8], o2[8]; unpack8(*(const u32x4*)(qp + ks * 16), f1); unpack8(*(const u32x4*)(qp + (ks + 2) * 16), f2);
; #pragma unroll
;               for (int e = 0; e < 8; ++e) { const int i = (ks - 8) * 16 + hh * 8 + e; const float cs = rp[2 * i], sn = rp[2 * i + 1];
;                   o1[e] = (f1[e] * cs - f2[e] * sn) * qs; o2[e] = (f1[e] * sn + f2[e] * cs) * qs; }
;               qf[ks] = __builtin_bit_cast(bf16x8, pack8(o1)); qf[ks + 2] = __builtin_bit_cast(bf16x8, pack8(o2)); asm volatile("" ::: "memory"); } }
	v_lshlrev_b32_e32 v30, 16, v35
	v_and_b32_e32 v31, 0xffff0000, v35
	v_lshlrev_b32_e32 v34, 16, v37
	v_and_b32_e32 v35, 0xffff0000, v37
	v_cvt_pk_bf16_f32 v117, v32, v33
	v_pk_mul_f32 v[6:7], v[6:7], s[28:29] op_sel_hi:[1,0]
	v_lshlrev_b32_e32 v32, 16, v36
	v_and_b32_e32 v33, 0xffff0000, v36
	v_pk_mul_f32 v[34:35], v[34:35], s[28:29] op_sel_hi:[1,0]
	v_pk_mul_f32 v[30:31], v[30:31], s[28:29] op_sel_hi:[1,0]
	v_pk_mul_f32 v[32:33], v[32:33], s[28:29] op_sel_hi:[1,0]
	v_cvt_pk_bf16_f32 v118, v6, v7
	v_cvt_pk_bf16_f32 v121, v34, v35
	v_lshlrev_b32_e32 v6, 16, v38
	v_and_b32_e32 v7, 0xffff0000, v38
	v_lshlrev_b32_e32 v34, 16, v39
	v_and_b32_e32 v35, 0xffff0000, v39
	v_lshlrev_b32_e32 v38, 16, v41
	v_and_b32_e32 v39, 0xffff0000, v41
	v_cvt_pk_bf16_f32 v119, v30, v31
	v_cvt_pk_bf16_f32 v120, v32, v33
	global_load_dwordx4 v[30:33], v[20:21], off offset:32
	v_pk_mul_f32 v[38:39], v[38:39], s[28:29] op_sel_hi:[1,0]
	v_pk_mul_f32 v[6:7], v[6:7], s[28:29] op_sel_hi:[1,0]
	v_lshlrev_b32_e32 v36, 16, v40
	v_and_b32_e32 v37, 0xffff0000, v40
	v_cvt_pk_bf16_f32 v125, v38, v39
	v_lshlrev_b32_e32 v38, 16, v2
	v_and_b32_e32 v39, 0xffff0000, v2
	v_lshlrev_b32_e32 v2, 16, v3
	v_and_b32_e32 v3, 0xffff0000, v3
	v_pk_mul_f32 v[34:35], v[34:35], s[28:29] op_sel_hi:[1,0]
	v_pk_mul_f32 v[36:37], v[36:37], s[28:29] op_sel_hi:[1,0]
	v_cvt_pk_bf16_f32 v122, v6, v7
	v_lshlrev_b32_e32 v6, 16, v0
	v_and_b32_e32 v7, 0xffff0000, v0
	v_lshlrev_b32_e32 v0, 16, v1
	v_and_b32_e32 v1, 0xffff0000, v1
	v_pk_mul_f32 v[2:3], v[2:3], s[28:29] op_sel_hi:[1,0]
	v_pk_mul_f32 v[44:45], v[44:45], s[28:29] op_sel_hi:[1,0]
	v_cvt_pk_bf16_f32 v116, v42, v43
	v_cvt_pk_bf16_f32 v123, v34, v35
	v_cvt_pk_bf16_f32 v124, v36, v37
	global_load_dwordx4 v[34:37], v[20:21], off offset:48
	v_pk_mul_f32 v[0:1], v[0:1], s[28:29] op_sel_hi:[1,0]
	v_cvt_pk_bf16_f32 v129, v2, v3
	s_waitcnt vmcnt(0) lgkmcnt(0)
	v_lshlrev_b32_e32 v42, 16, v12
	v_and_b32_e32 v43, 0xffff0000, v8
	v_mov_b32_e32 v2, v16
	v_mov_b32_e32 v3, v19
	v_cvt_pk_bf16_f32 v102, v44, v45
	v_cvt_pk_bf16_f32 v127, v0, v1
	v_mov_b32_e32 v0, v17
	v_mov_b32_e32 v1, v18
	v_lshlrev_b32_e32 v44, 16, v8
	v_and_b32_e32 v45, 0xffff0000, v12
	v_pk_mul_f32 v[2:3], v[2:3], v[42:43]
	v_pk_mul_f32 v[46:47], v[46:47], s[28:29] op_sel_hi:[1,0]
	v_pk_mul_f32 v[6:7], v[6:7], s[28:29] op_sel_hi:[1,0]
	v_pk_mul_f32 v[38:39], v[38:39], s[28:29] op_sel_hi:[1,0]
	v_pk_fma_f32 v[0:1], v[0:1], v[44:45], v[2:3]
	v_cvt_pk_bf16_f32 v104, v46, v47
	v_cvt_pk_bf16_f32 v126, v6, v7
	v_cvt_pk_bf16_f32 v128, v38, v39
	v_pk_mul_f32 v[46:47], v[0:1], s[28:29] op_sel_hi:[1,0]
	global_load_dwordx4 v[38:41], v[20:21], off offset:128
	global_load_dwordx4 v[0:3], v[4:5], off offset:288
	s_nop 0
	global_load_dwordx4 v[4:7], v[4:5], off offset:352
	v_mov_b32_e32 v49, v18
	v_mov_b32_e32 v51, v43
	v_mov_b32_e32 v18, v17
	v_mov_b32_e32 v43, v45
	v_mov_b32_e32 v48, v16
	v_mov_b32_e32 v50, v44
	v_pk_mul_f32 v[16:17], v[18:19], v[42:43]
	v_lshlrev_b32_e32 v44, 16, v13
	v_pk_fma_f32 v[16:17], v[48:49], v[50:51], v[16:17] neg_lo:[0,0,1] neg_hi:[0,0,1]
	v_and_b32_e32 v45, 0xffff0000, v9
	v_lshlrev_b32_e32 v8, 16, v9
	v_and_b32_e32 v9, 0xffff0000, v13
	v_mov_b32_e32 v12, v26
	v_mov_b32_e32 v13, v29
	v_pk_mul_f32 v[42:43], v[16:17], s[28:29] op_sel_hi:[1,0]
	v_mov_b32_e32 v16, v27
	v_mov_b32_e32 v17, v28
	v_pk_mul_f32 v[12:13], v[12:13], v[44:45]
	v_mov_b32_e32 v49, v28
	v_mov_b32_e32 v51, v45
	v_mov_b32_e32 v28, v27
	v_mov_b32_e32 v45, v9
	v_pk_fma_f32 v[12:13], v[16:17], v[8:9], v[12:13]
	v_mov_b32_e32 v48, v26
	v_mov_b32_e32 v50, v8
	v_pk_mul_f32 v[8:9], v[28:29], v[44:45]
	v_lshlrev_b32_e32 v28, 16, v14
	v_pk_fma_f32 v[8:9], v[48:49], v[50:51], v[8:9] neg_lo:[0,0,1] neg_hi:[0,0,1]
	v_and_b32_e32 v29, 0xffff0000, v10
	v_lshlrev_b32_e32 v44, 16, v10
	v_and_b32_e32 v45, 0xffff0000, v14
	v_mov_b32_e32 v51, v29
	v_mov_b32_e32 v50, v44
	v_lshlrev_b32_e32 v10, 16, v11
	v_mov_b32_e32 v48, v30
	v_mov_b32_e32 v49, v33
	v_mov_b32_e32 v26, v31
	v_mov_b32_e32 v27, v32
	v_pk_mul_f32 v[48:49], v[48:49], v[28:29]
	v_mov_b32_e32 v29, v45
	v_pk_fma_f32 v[26:27], v[26:27], v[44:45], v[48:49]
	v_mov_b32_e32 v49, v32
	v_mov_b32_e32 v32, v31
	v_mov_b32_e32 v48, v30
	v_pk_mul_f32 v[28:29], v[32:33], v[28:29]
	v_lshlrev_b32_e32 v32, 16, v15
	v_and_b32_e32 v33, 0xffff0000, v11
	v_and_b32_e32 v11, 0xffff0000, v15
	v_pk_fma_f32 v[28:29], v[48:49], v[50:51], v[28:29] neg_lo:[0,0,1] neg_hi:[0,0,1]
	v_mov_b32_e32 v45, v33
	v_pk_mul_f32 v[26:27], v[26:27], s[28:29] op_sel_hi:[1,0]
	v_pk_mul_f32 v[28:29], v[28:29], s[28:29] op_sel_hi:[1,0]
	v_mov_b32_e32 v44, v10
	v_pk_mul_f32 v[12:13], v[12:13], s[28:29] op_sel_hi:[1,0]
	global_load_dwordx4 v[16:19], v[20:21], off offset:144
	v_cvt_pk_bf16_f32 v132, v28, v29
	v_mov_b32_e32 v14, v34
	v_mov_b32_e32 v15, v37
	v_mov_b32_e32 v30, v35
	v_mov_b32_e32 v31, v36
	v_pk_mul_f32 v[14:15], v[14:15], v[32:33]
	v_mov_b32_e32 v36, v35
	v_mov_b32_e32 v33, v11
	v_pk_fma_f32 v[14:15], v[30:31], v[10:11], v[14:15]
	v_mov_b32_e32 v30, v34
	v_pk_mul_f32 v[10:11], v[36:37], v[32:33]
	v_pk_mul_f32 v[14:15], v[14:15], s[28:29] op_sel_hi:[1,0]
	v_pk_fma_f32 v[10:11], v[30:31], v[44:45], v[10:11] neg_lo:[0,0,1] neg_hi:[0,0,1]
	v_cvt_pk_bf16_f32 v136, v26, v27
	v_pk_mul_f32 v[8:9], v[8:9], s[28:29] op_sel_hi:[1,0]
	v_pk_mul_f32 v[10:11], v[10:11], s[28:29] op_sel_hi:[1,0]
	v_cvt_pk_bf16_f32 v135, v12, v13
	v_cvt_pk_bf16_f32 v137, v14, v15
	v_cvt_pk_bf16_f32 v131, v8, v9
	v_cvt_pk_bf16_f32 v133, v10, v11
	global_load_dwordx4 v[8:11], v[20:21], off offset:160
	v_ashrrev_i32_e32 v52, 3, v23
	s_waitcnt vmcnt(0) lgkmcnt(0)
; __device__ __forceinline__ void unpack8(const u32x4 w, float (&f)[8]) { f[0] = bflo(w.x); f[1] = bfhi(w.x); f[2] = bflo(w.y); f[3] = bfhi(w.y); f[4] = bflo(w.z); f[5] = bfhi(w.z); f[6] = bflo(w.w); f[7] = bfhi(w.w); }
; __device__ __forceinline__ u32x4 pack8(const float (&f)[8]) { u32x4 w; w.x = pk_bf16(f[0], f[1]); w.y = pk_bf16(f[2], f[3]); w.z = pk_bf16(f[4], f[5]); w.w = pk_bf16(f[6], f[7]); return w; }
; #define AT_ISSUE(kt) do { const char* p_ = kvb + (size_t)(kt) * (64 * 3072 * 2); const char* q_ = kpb + (size_t)(kt) * (64 * 64 * 2); \
;         sk[0] = *(const u32x4*)(p_ + kvo); sk[1] = *(const u32x4*)(p_ + (kvo + 32u * 3072u * 2u)); sv[0] = *(const u32x4*)(p_ + (kvo + 256u)); sv[1] = *(const u32x4*)(p_ + (kvo + 32u * 3072u * 2u + 256u)); \
;         sk[2] = *(const u32x4*)(q_ + kpo); } while (0)
; __device__ __forceinline__ void attn_phase(LAS unsigned char* lds, const bf16* Q, const bf16* KV, const bf16* KPE, const float* rope, bf16* mix, int bid, int G, int tid) {
;     ...
;           for (int ks = 8; ks < 10; ++ks) { float f1[8], f2[8], o1[8], o2[8]; unpack8(*(const u32x4*)(qp + ks * 16), f1); unpack8(*(const u32x4*)(qp + (ks + 2) * 16), f2);
; #pragma unroll
;               for (int e = 0; e < 8; ++e) { const int i = (ks - 8) * 16 + hh * 8 + e; const float cs = rp[2 * i], sn = rp[2 * i + 1];
;                   o1[e] = (f1[e] * cs - f2[e] * sn) * qs; o2[e] = (f1[e] * sn + f2[e] * cs) * qs; }
;               qf[ks] = __builtin_bit_cast(bf16x8, pack8(o1)); qf[ks + 2] = __builtin_bit_cast(bf16x8, pack8(o2)); asm volatile("" ::: "memory"); } }
;         f32x16 O[4];
; #pragma unroll
;         for (int i = 0; i < 4; ++i)
; #pragma unroll
;             for (int e = 0; e < 16; ++e) O[i][e] = 0.f;
;         float mrun = -1e30f, lrun = 0.f;
;         u32x4 sk[3], sv[2];
;         const char* kvb = (const char*)(KV + (size_t)mrow0 * 3072 + h * 256); const char* kpb = (const char*)(KPE + (size_t)mrow0 * 64);
;         const unsigned kvo = (unsigned)(sr16 * 3072 + sc16 * 8) * 2u, kpo = (unsigned)(sr8 * 64 + sc8 * 8) * 2u;
;     ...
;         AT_ISSUE(0); AT_COMMIT(lds);
;         __syncthreads();
	v_mov_b32_e32 v28, v38
	v_and_b32_e32 v27, 0xffff0000, v0
	v_lshlrev_b32_e32 v26, 16, v4
	v_mov_b32_e32 v29, v41
	v_mov_b32_e32 v12, v39
	v_mov_b32_e32 v13, v40
	v_lshlrev_b32_e32 v14, 16, v0
	v_and_b32_e32 v15, 0xffff0000, v4
	v_pk_mul_f32 v[28:29], v[28:29], v[26:27]
	v_mov_b32_e32 v31, v40
	v_pk_fma_f32 v[12:13], v[12:13], v[14:15], v[28:29]
	v_mov_b32_e32 v33, v27
	v_mov_b32_e32 v40, v39
	v_mov_b32_e32 v27, v15
	v_lshlrev_b32_e32 v0, 4, v23
	v_pk_mul_f32 v[28:29], v[12:13], s[28:29] op_sel_hi:[1,0]
	v_mov_b32_e32 v30, v38
	v_mov_b32_e32 v32, v14
	global_load_dwordx4 v[12:15], v[20:21], off offset:176
	v_pk_mul_f32 v[20:21], v[40:41], v[26:27]
	v_and_b32_e32 v187, 0xf0, v0
	v_mul_lo_u32 v4, v25, s11
	v_pk_fma_f32 v[20:21], v[30:31], v[32:33], v[20:21] neg_lo:[0,0,1] neg_hi:[0,0,1]
	v_or_b32_e32 v30, v187, v4
	v_mov_b32_e32 v31, v97
	v_lshl_add_u64 v[34:35], s[14:15], 0, v[30:31]
	v_and_b32_e32 v188, 0x70, v0
	global_load_dwordx4 v[138:141], v[34:35], off
	global_load_dwordx4 v[146:149], v[34:35], off offset:256
	v_add_u32_e32 v36, 0x30000, v30
	v_mov_b32_e32 v37, v97
	v_add_u32_e32 v34, 0x30100, v30
	v_mov_b32_e32 v35, v97
	v_lshl_or_b32 v32, v52, 7, v188
	v_lshl_add_u64 v[38:39], s[14:15], 0, v[36:37]
	v_mov_b32_e32 v33, v97
	v_lshl_add_u64 v[40:41], s[14:15], 0, v[34:35]
	global_load_dwordx4 v[142:145], v[38:39], off
	global_load_dwordx4 v[154:157], v[40:41], off
	v_lshl_add_u64 v[38:39], s[30:31], 0, v[32:33]
	global_load_dwordx4 v[150:153], v[38:39], off
	v_lshlrev_b32_e32 v38, 16, v5
	v_and_b32_e32 v39, 0xffff0000, v1
	v_lshlrev_b32_e32 v0, 16, v1
	v_and_b32_e32 v1, 0xffff0000, v5
	v_mov_b32_e32 v41, v39
	v_mov_b32_e32 v40, v0
	s_movk_i32 s11, 0x190
	v_mul_lo_u32 v190, v25, s11
	v_mul_lo_u32 v192, v52, s11
	s_movk_i32 s11, 0x140
	v_mul_lo_u32 v193, v25, s11
	s_movk_i32 s11, 0xffb0
	v_pk_mul_f32 v[20:21], v[20:21], s[28:29] op_sel_hi:[1,0]
	v_cvt_pk_bf16_f32 v130, v42, v43
	v_cvt_pk_bf16_f32 v134, v46, v47
	v_mov_b32_e32 v4, v16
	v_mov_b32_e32 v5, v19
	v_mov_b32_e32 v26, v17
	v_mov_b32_e32 v27, v18
	v_pk_mul_f32 v[4:5], v[4:5], v[38:39]
	v_mov_b32_e32 v18, v17
	v_mov_b32_e32 v39, v1
	v_pk_fma_f32 v[4:5], v[26:27], v[0:1], v[4:5]
	v_mov_b32_e32 v26, v16
	v_pk_mul_f32 v[0:1], v[18:19], v[38:39]
	v_lshlrev_b32_e32 v18, 16, v6
	v_and_b32_e32 v19, 0xffff0000, v2
	v_pk_fma_f32 v[0:1], v[26:27], v[40:41], v[0:1] neg_lo:[0,0,1] neg_hi:[0,0,1]
	v_lshlrev_b32_e32 v26, 16, v2
	v_and_b32_e32 v27, 0xffff0000, v6
	v_mov_b32_e32 v41, v19
	v_lshlrev_b32_e32 v2, 16, v3
	v_pk_mul_f32 v[0:1], v[0:1], s[28:29] op_sel_hi:[1,0]
	v_mov_b32_e32 v40, v26
	v_cvt_pk_bf16_f32 v159, v0, v1
	v_add3_u32 v0, 0, v190, v187
	v_mov_b32_e32 v38, v8
	v_mov_b32_e32 v39, v11
	v_mov_b32_e32 v16, v9
	v_mov_b32_e32 v17, v10
	v_pk_mul_f32 v[38:39], v[38:39], v[18:19]
	v_mov_b32_e32 v19, v27
	v_pk_fma_f32 v[16:17], v[16:17], v[26:27], v[38:39]
	v_mov_b32_e32 v39, v10
	v_mov_b32_e32 v10, v9
	v_mov_b32_e32 v38, v8
	v_pk_mul_f32 v[8:9], v[10:11], v[18:19]
	v_lshlrev_b32_e32 v18, 16, v7
	v_and_b32_e32 v19, 0xffff0000, v3
	v_and_b32_e32 v3, 0xffff0000, v7
	v_mov_b32_e32 v27, v19
	v_mov_b32_e32 v26, v2
	v_add3_u32 v1, 0, v192, v188
	v_pk_fma_f32 v[8:9], v[38:39], v[40:41], v[8:9] neg_lo:[0,0,1] neg_hi:[0,0,1]
	v_pk_mul_f32 v[4:5], v[4:5], s[28:29] op_sel_hi:[1,0]
	v_pk_mul_f32 v[16:17], v[16:17], s[28:29] op_sel_hi:[1,0]
	s_waitcnt vmcnt(0) lgkmcnt(0)
	v_mov_b32_e32 v6, v12
	v_mov_b32_e32 v7, v15
	v_mov_b32_e32 v10, v13
	v_mov_b32_e32 v11, v14
	v_pk_mul_f32 v[6:7], v[6:7], v[18:19]
	v_mov_b32_e32 v14, v13
	v_mov_b32_e32 v19, v3
	v_pk_fma_f32 v[6:7], v[10:11], v[2:3], v[6:7]
	v_mov_b32_e32 v10, v12
	v_pk_mul_f32 v[2:3], v[14:15], v[18:19]
	ds_write_b128 v0, v[138:141]
	v_pk_fma_f32 v[2:3], v[10:11], v[26:27], v[2:3] neg_lo:[0,0,1] neg_hi:[0,0,1]
	v_pk_mul_f32 v[8:9], v[8:9], s[28:29] op_sel_hi:[1,0]
	v_pk_mul_f32 v[2:3], v[2:3], s[28:29] op_sel_hi:[1,0]
	v_pk_mul_f32 v[6:7], v[6:7], s[28:29] op_sel_hi:[1,0]
	v_cvt_pk_bf16_f32 v161, v2, v3
	v_mov_b32_e32 v14, v97
	v_mov_b32_e32 v15, v97
	v_cvt_pk_bf16_f32 v158, v20, v21
	v_cvt_pk_bf16_f32 v160, v8, v9
	ds_write_b128 v0, v[142:145] offset:12800
	v_cvt_pk_bf16_f32 v162, v28, v29
	v_cvt_pk_bf16_f32 v163, v4, v5
	ds_write_b128 v1, v[150:153] offset:256
	v_mul_lo_u32 v1, v25, s11
	s_movk_i32 s11, 0x3200
	v_add_u32_e32 v2, v0, v1
	v_add3_u32 v0, v0, s11, v1
	s_or_b32 s11, s8, 31
	s_add_u32 s4, s4, 0x26a02000
	s_addc_u32 s5, s5, 0
	ds_write_b128 v0, v[154:157] offset:48640
	v_lshrrev_b32_e32 v0, 2, v23
	s_add_u32 s0, s17, s0
	v_and_or_b32 v0, v0, 3, v189
	s_addc_u32 s1, s19, s1
	v_mul_u32_u24_e32 v204, 0x140, v0
	v_and_b32_e32 v0, 16, v23
	v_lshlrev_b32_e32 v1, 2, v23
	v_lshl_add_u64 v[176:177], s[4:5], 0, v[32:33]
	s_add_u32 s4, s0, 0x27660000
	v_and_or_b32 v0, v1, 12, v0
	s_addc_u32 s5, s1, 0
	v_cvt_pk_bf16_f32 v164, v16, v17
	v_cvt_pk_bf16_f32 v165, v6, v7
	ds_write_b128 v2, v[146:149] offset:51200
	v_lshlrev_b32_e32 v205, 1, v0
	v_lshl_add_u64 v[178:179], s[4:5], 0, v[34:35]
	v_lshl_add_u64 v[180:181], s[4:5], 0, v[36:37]
	v_lshl_add_u64 v[182:183], s[0:1], 0, v[30:31]
	v_mov_b32_e32 v0, v97
	v_mov_b32_e32 v1, v97
	v_mov_b32_e32 v2, v97
	v_mov_b32_e32 v3, v97
	v_mov_b32_e32 v4, v97
	v_mov_b32_e32 v5, v97
	v_mov_b32_e32 v6, v97
	v_mov_b32_e32 v7, v97
	v_mov_b32_e32 v8, v97
	v_mov_b32_e32 v9, v97
	v_mov_b32_e32 v10, v97
	v_mov_b32_e32 v11, v97
	v_mov_b32_e32 v12, v97
	v_mov_b32_e32 v13, v97
	v_mov_b64_e32 v[30:31], v[14:15]
	v_mov_b64_e32 v[46:47], v[14:15]
	v_mov_b64_e32 v[62:63], v[14:15]
	v_add_u32_e32 v191, 0x3200, v190
	v_add_u32_e32 v202, 0x2800, v193
	s_mov_b32 s4, 0
	s_mov_b32 s0, 63
	v_mov_b64_e32 v[28:29], v[12:13]
	v_mov_b64_e32 v[26:27], v[10:11]
	v_mov_b64_e32 v[24:25], v[8:9]
	v_mov_b64_e32 v[22:23], v[6:7]
	v_mov_b64_e32 v[20:21], v[4:5]
	v_mov_b64_e32 v[18:19], v[2:3]
	v_mov_b64_e32 v[16:17], v[0:1]
	v_mov_b64_e32 v[44:45], v[12:13]
	v_mov_b64_e32 v[42:43], v[10:11]
	v_mov_b64_e32 v[40:41], v[8:9]
	v_mov_b64_e32 v[38:39], v[6:7]
	v_mov_b64_e32 v[36:37], v[4:5]
	v_mov_b64_e32 v[34:35], v[2:3]
	v_mov_b64_e32 v[32:33], v[0:1]
	v_mov_b64_e32 v[60:61], v[12:13]
	v_mov_b64_e32 v[58:59], v[10:11]
	v_mov_b64_e32 v[56:57], v[8:9]
	v_mov_b64_e32 v[54:55], v[6:7]
	v_mov_b64_e32 v[52:53], v[4:5]
	v_mov_b64_e32 v[50:51], v[2:3]
	v_mov_b64_e32 v[48:49], v[0:1]
	s_waitcnt lgkmcnt(0)
	s_barrier
	v_readfirstlane_b32 s17, v186
	s_movk_i32 s14, 0x6400
	s_lshr_b32 s17, s17, 8
	s_and_b32 s17, s17, 1
; #define LAS __attribute__((address_space(3)))
; #define AT_ISSUE(kt) do { const char* p_ = kvb + (size_t)(kt) * (64 * 3072 * 2); const char* q_ = kpb + (size_t)(kt) * (64 * 64 * 2); \
;         sk[0] = *(const u32x4*)(p_ + kvo); sk[1] = *(const u32x4*)(p_ + (kvo + 32u * 3072u * 2u)); sv[0] = *(const u32x4*)(p_ + (kvo + 256u)); sv[1] = *(const u32x4*)(p_ + (kvo + 32u * 3072u * 2u + 256u)); \
;         sk[2] = *(const u32x4*)(q_ + kpo); } while (0)
; #define AT_LDK(buf, grp) do { _Pragma("unroll") for (int q_ = 0; q_ < 2; ++q_) { kf[buf][2 * q_] = *(const LAS bf16x8*)(ka + ((grp) * 2 + q_) * 32); kf[buf][2 * q_ + 1] = *(const LAS bf16x8*)(ka + 32 * AT_KROW + ((grp) * 2 + q_) * 32); } } while (0)
; __device__ __forceinline__ void attn_phase(LAS unsigned char* lds, const bf16* Q, const bf16* KV, const bf16* KPE, const float* rope, bf16* mix, int bid, int G, int tid) {
;     ...
;         for (int kt = 0; kt < ntiles; ++kt) {
;             if (kt + 1 < ntiles) AT_ISSUE(kt + 1);
;             const int key0 = kt * 64;
;             const LAS unsigned char* kb_ = lds + (kt & 1) * AT_BUF; const LAS unsigned char* vb_ = kb_ + AT_KB;
;             if (key0 <= qlo + 31) {
;                 f32x16 S0, S1;
; #pragma unroll
;                 for (int e = 0; e < 16; ++e) { S0[e] = 0.f; S1[e] = 0.f; }
;                 const LAS unsigned char* ka = kb_ + l32 * AT_KROW + hh * 16;
;                 bf16x8 kf[2][4];
;     ...
;                 AT_LDK(0, 0); __builtin_amdgcn_sched_barrier(0);
; #pragma unroll
;                 for (int grp = 0; grp < 6; ++grp) {
;                     if (grp < 5) { AT_LDK((grp + 1) & 1, grp + 1); }
;                     __builtin_amdgcn_sched_barrier(0);
;                     __builtin_amdgcn_s_setprio(1);
; #pragma unroll
;                     for (int q_ = 0; q_ < 2; ++q_) {
;                         S0 = __builtin_amdgcn_mfma_f32_32x32x16_bf16(kf[grp & 1][2 * q_], qf[grp * 2 + q_], S0, 0, 0, 0);
;                         S1 = __builtin_amdgcn_mfma_f32_32x32x16_bf16(kf[grp & 1][2 * q_ + 1], qf[grp * 2 + q_], S1, 0, 0, 0); }
;                     __builtin_amdgcn_s_setprio(0);
;                     __builtin_amdgcn_sched_barrier(0); }
.LBB0_251:
	s_add_i32 s1, s4, 1
	s_cmp_lt_i32 s1, s9
	s_cselect_b64 s[34:35], -1, 0
	s_cmp_ge_i32 s1, s9
	s_cbranch_scc1 .LBB0_253
	s_cmp_eq_u32 s17, 0
	s_cbranch_scc1 .Latt_issue
	s_cmp_lg_u32 s4, 0
	s_cbranch_scc1 .LBB0_253
.Latt_issue:
	v_lshl_add_u64 v[64:65], s[88:89], 0, v[182:183]
	v_add_co_u32_e32 v64, vcc, 0x27660000, v64
	v_lshl_add_u64 v[66:67], s[88:89], 0, v[180:181]
	s_nop 0
	v_addc_co_u32_e32 v65, vcc, 0, v65, vcc
	s_waitcnt vmcnt(0)
	global_load_dwordx4 v[138:141], v[64:65], off
	global_load_dwordx4 v[146:149], v[64:65], off offset:256
	v_lshl_add_u64 v[64:65], s[88:89], 0, v[178:179]
	global_load_dwordx4 v[142:145], v[66:67], off
	global_load_dwordx4 v[154:157], v[64:65], off
	v_lshl_add_u64 v[64:65], s[88:89], 0, v[176:177]
	global_load_dwordx4 v[150:153], v[64:65], off
.LBB0_253:
	s_sub_i32 s5, s0, 63
	s_cmp_gt_i32 s5, s11
	s_cbranch_scc1 .LBB0_259
	s_bitcmp1_b32 s4, 0
	s_cselect_b32 s4, 0x6400, 0
	v_add3_u32 v236, s4, v203, v96
	ds_read_b128 v[64:67], v236
	ds_read_b128 v[166:169], v236 offset:32
	ds_read_b128 v[68:71], v236 offset:12800
	ds_read_b128 v[170:173], v236 offset:12832
	ds_read_b128 v[208:211], v236 offset:64
	ds_read_b128 v[212:215], v236 offset:96
	ds_read_b128 v[228:231], v236 offset:12864
	ds_read_b128 v[232:235], v236 offset:12896
	s_setprio 1
	s_waitcnt lgkmcnt(0)
	v_mfma_f32_32x32x16_bf16 v[80:95], v[64:67], v[98:101], 0
	v_mfma_f32_32x32x16_bf16 v[64:79], v[68:71], v[98:101], 0
	v_mfma_f32_32x32x16_bf16 v[80:95], v[166:169], v[102:105], v[80:95]
	v_mfma_f32_32x32x16_bf16 v[64:79], v[170:173], v[102:105], v[64:79]
	s_setprio 0
	ds_read_b128 v[166:169], v236 offset:128
	ds_read_b128 v[170:173], v236 offset:160
	ds_read_b128 v[242:245], v236 offset:12928
	ds_read_b128 v[246:249], v236 offset:12960
	s_setprio 1
	v_mfma_f32_32x32x16_bf16 v[80:95], v[208:211], v[106:109], v[80:95]
	v_mfma_f32_32x32x16_bf16 v[64:79], v[228:231], v[106:109], v[64:79]
	v_mfma_f32_32x32x16_bf16 v[80:95], v[212:215], v[110:113], v[80:95]
	v_mfma_f32_32x32x16_bf16 v[64:79], v[232:235], v[110:113], v[64:79]
	s_setprio 0
	ds_read_b128 v[208:211], v236 offset:192
	ds_read_b128 v[212:215], v236 offset:224
	ds_read_b128 v[228:231], v236 offset:12992
	ds_read_b128 v[232:235], v236 offset:13024
	s_setprio 1
	s_waitcnt lgkmcnt(0)
	v_mfma_f32_32x32x16_bf16 v[80:95], v[166:169], v[114:117], v[80:95]
	v_mfma_f32_32x32x16_bf16 v[64:79], v[242:245], v[114:117], v[64:79]
	v_mfma_f32_32x32x16_bf16 v[80:95], v[170:173], v[118:121], v[80:95]
	v_mfma_f32_32x32x16_bf16 v[64:79], v[246:249], v[118:121], v[64:79]
	s_setprio 0
	ds_read_b128 v[166:169], v236 offset:256
	ds_read_b128 v[170:173], v236 offset:288
	ds_read_b128 v[242:245], v236 offset:13056
	ds_read_b128 v[246:249], v236 offset:13088
	s_setprio 1
	v_mfma_f32_32x32x16_bf16 v[80:95], v[208:211], v[122:125], v[80:95]
	v_mfma_f32_32x32x16_bf16 v[64:79], v[228:231], v[122:125], v[64:79]
	v_mfma_f32_32x32x16_bf16 v[80:95], v[212:215], v[126:129], v[80:95]
	v_mfma_f32_32x32x16_bf16 v[64:79], v[232:235], v[126:129], v[64:79]
	s_setprio 0
	ds_read_b128 v[208:211], v236 offset:320
	ds_read_b128 v[212:215], v236 offset:352
	ds_read_b128 v[228:231], v236 offset:13120
	ds_read_b128 v[232:235], v236 offset:13152
	s_setprio 1
	s_waitcnt lgkmcnt(0)
	v_mfma_f32_32x32x16_bf16 v[80:95], v[166:169], v[130:133], v[80:95]
	v_mfma_f32_32x32x16_bf16 v[64:79], v[242:245], v[130:133], v[64:79]
	v_mfma_f32_32x32x16_bf16 v[80:95], v[170:173], v[158:161], v[80:95]
	v_mfma_f32_32x32x16_bf16 v[64:79], v[246:249], v[158:161], v[64:79]
	s_setprio 0
	s_setprio 1
	s_setprio 0
	v_mfma_f32_32x32x16_bf16 v[80:95], v[208:211], v[134:137], v[80:95]
	v_add_u32_e32 v166, s14, v204
	v_add_u32_e32 v208, v166, v205
	ds_read_b64_tr_b16 v[170:171], v208 offset:25600
	ds_read_b64_tr_b16 v[172:173], v208 offset:28160
	ds_read_b64_tr_b16 v[168:169], v208 offset:28224
	ds_read_b64_tr_b16 v[166:167], v208 offset:25664
	v_mfma_f32_32x32x16_bf16 v[64:79], v[228:231], v[134:137], v[64:79]
	v_mfma_f32_32x32x16_bf16 v[80:95], v[212:215], v[162:165], v[80:95]
	v_mfma_f32_32x32x16_bf16 v[64:79], v[232:235], v[162:165], v[64:79]
	s_cmp_eq_u32 s17, 0
	s_cbranch_scc1 .Latt_xa
	s_andn2_b64 vcc, exec, s[34:35]
	s_cbranch_vccnz .Latt_xnc_a
	s_bitcmp1_b32 s1, 0
	s_cselect_b32 s4, 0x6400, 0
	s_add_i32 s15, s14, 0x5000
	s_cmp_gt_u32 s15, 0x10400
	s_cselect_b32 s15, 0x6400, s15
	v_add3_u32 v250, s4, v190, v187
	s_waitcnt vmcnt(0) lgkmcnt(0)
	ds_write_b128 v250, v[138:141]
	v_add3_u32 v250, s4, v191, v187
	ds_write_b128 v250, v[142:145]
	v_add3_u32 v250, s4, v192, v188
	ds_write_b128 v250, v[150:153] offset:256
	v_add3_u32 v250, s15, v193, v187
	ds_write_b128 v250, v[146:149] offset:25600
	v_add3_u32 v250, s15, v202, v187
	ds_write_b128 v250, v[154:157] offset:25600
; __device__ __forceinline__ void attn_phase(LAS unsigned char* lds, const bf16* Q, const bf16* KV, const bf16* KPE, const float* rope, bf16* mix, int bid, int G, int tid) {
;     ...
;                 if (key0 + 63 > qlo) { const int qq = qlo + l32;
; #pragma unroll
;                     for (int e = 0; e < 16; ++e) { const int key = key0 + 8 * (e >> 2) + 4 * hh + (e & 3);
;                         if (key > qq) S0[e] = -1e30f; if (key + 32 > qq) S1[e] = -1e30f; } }
.Latt_xnc_a:
	s_waitcnt lgkmcnt(0)
	s_barrier
	s_add_i32 s15, s1, 1
	s_cmp_ge_i32 s15, s9
	s_cbranch_scc1 .Latt_xni_a
	s_add_u32 s30, s88, 0x60000
	s_addc_u32 s31, s89, 0
	v_lshl_add_u64 v[250:251], s[30:31], 0, v[182:183]
	v_add_co_u32_e32 v250, vcc, 0x27660000, v250
	s_nop 1
	v_addc_co_u32_e32 v251, vcc, 0, v251, vcc
	global_load_dwordx4 v[138:141], v[250:251], off
	global_load_dwordx4 v[146:149], v[250:251], off offset:256
	v_lshl_add_u64 v[250:251], s[30:31], 0, v[180:181]
	global_load_dwordx4 v[142:145], v[250:251], off
	v_lshl_add_u64 v[250:251], s[30:31], 0, v[178:179]
	global_load_dwordx4 v[154:157], v[250:251], off
	s_add_u32 s30, s88, 0x2000
	s_addc_u32 s31, s89, 0
	v_lshl_add_u64 v[250:251], s[30:31], 0, v[176:177]
	global_load_dwordx4 v[150:153], v[250:251], off
.Latt_xni_a:
.Latt_xa:
	s_cmp_le_i32 s0, s8
	s_cbranch_scc1 .LBB0_256
	v_add_u32_e32 v209, s0, v189
	v_subrev_u32_e32 v211, 31, v209
	v_subrev_u32_e32 v210, 63, v209
	v_cmp_le_i32_e32 vcc, v211, v206
	s_nop 5
	v_cndmask_b32_e32 v64, v224, v64, vcc
	v_cmp_lt_i32_e32 vcc, v210, v206
	s_nop 1
	v_cndmask_b32_e32 v81, v224, v81, vcc
	v_cmp_le_i32_e32 vcc, v210, v206
	v_subrev_u32_e32 v210, 30, v209
	s_nop 0
	v_cndmask_b32_e32 v80, v224, v80, vcc
	v_cmp_le_i32_e32 vcc, v210, v206
	v_subrev_u32_e32 v210, 61, v209
	s_nop 0
	v_cndmask_b32_e32 v65, v224, v65, vcc
	v_cmp_le_i32_e32 vcc, v210, v206
	v_subrev_u32_e32 v210, 29, v209
	s_nop 0
	v_cndmask_b32_e32 v82, v224, v82, vcc
	v_cmp_le_i32_e32 vcc, v210, v206
	v_subrev_u32_e32 v210, 60, v209
	s_nop 0
	v_cndmask_b32_e32 v66, v224, v66, vcc
	v_cmp_le_i32_e32 vcc, v210, v206
	v_subrev_u32_e32 v210, 28, v209
	s_nop 0
	v_cndmask_b32_e32 v83, v224, v83, vcc
	v_cmp_le_i32_e32 vcc, v210, v206
	v_subrev_u32_e32 v210, 55, v209
	s_nop 0
	v_cndmask_b32_e32 v67, v224, v67, vcc
	v_cmp_le_i32_e32 vcc, v210, v206
	v_subrev_u32_e32 v210, 23, v209
	s_nop 0
	v_cndmask_b32_e32 v84, v224, v84, vcc
	v_cmp_le_i32_e32 vcc, v210, v206
	v_subrev_u32_e32 v210, 54, v209
	s_nop 0
	v_cndmask_b32_e32 v68, v224, v68, vcc
	v_cmp_le_i32_e32 vcc, v210, v206
	v_subrev_u32_e32 v210, 22, v209
	s_nop 0
	v_cndmask_b32_e32 v85, v224, v85, vcc
	v_cmp_le_i32_e32 vcc, v210, v206
	v_subrev_u32_e32 v210, 53, v209
	s_nop 0
	v_cndmask_b32_e32 v69, v224, v69, vcc
	v_cmp_le_i32_e32 vcc, v210, v206
	v_subrev_u32_e32 v210, 21, v209
	s_nop 0
	v_cndmask_b32_e32 v86, v224, v86, vcc
	v_cmp_le_i32_e32 vcc, v210, v206
	v_subrev_u32_e32 v210, 52, v209
	s_nop 0
	v_cndmask_b32_e32 v70, v224, v70, vcc
	v_cmp_le_i32_e32 vcc, v210, v206
	v_subrev_u32_e32 v210, 20, v209
	s_nop 0
	v_cndmask_b32_e32 v87, v224, v87, vcc
	v_cmp_le_i32_e32 vcc, v210, v206
	v_subrev_u32_e32 v210, 47, v209
	s_nop 0
	v_cndmask_b32_e32 v71, v224, v71, vcc
	v_cmp_le_i32_e32 vcc, v210, v206
	v_add_u32_e32 v210, -15, v209
	s_nop 0
	v_cndmask_b32_e32 v88, v224, v88, vcc
	v_cmp_le_i32_e32 vcc, v210, v206
	v_subrev_u32_e32 v210, 46, v209
	s_nop 0
	v_cndmask_b32_e32 v72, v224, v72, vcc
	v_cmp_le_i32_e32 vcc, v210, v206
	v_add_u32_e32 v210, -14, v209
	s_nop 0
	v_cndmask_b32_e32 v89, v224, v89, vcc
	v_cmp_le_i32_e32 vcc, v210, v206
	v_subrev_u32_e32 v210, 45, v209
	s_nop 0
	v_cndmask_b32_e32 v73, v224, v73, vcc
	v_cmp_le_i32_e32 vcc, v210, v206
	v_add_u32_e32 v210, -13, v209
	s_nop 0
	v_cndmask_b32_e32 v90, v224, v90, vcc
	v_cmp_le_i32_e32 vcc, v210, v206
	v_subrev_u32_e32 v210, 44, v209
	s_nop 0
	v_cndmask_b32_e32 v74, v224, v74, vcc
	v_cmp_le_i32_e32 vcc, v210, v206
	v_add_u32_e32 v210, -12, v209
	s_nop 0
	v_cndmask_b32_e32 v91, v224, v91, vcc
	v_cmp_le_i32_e32 vcc, v210, v206
	v_subrev_u32_e32 v210, 39, v209
	s_nop 0
	v_cndmask_b32_e32 v75, v224, v75, vcc
	v_cmp_le_i32_e32 vcc, v210, v206
	v_add_u32_e32 v210, -7, v209
	s_nop 0
	v_cndmask_b32_e32 v92, v224, v92, vcc
	v_cmp_le_i32_e32 vcc, v210, v206
	v_subrev_u32_e32 v210, 38, v209
	s_nop 0
	v_cndmask_b32_e32 v76, v224, v76, vcc
	v_cmp_le_i32_e32 vcc, v210, v206
	v_add_u32_e32 v210, -6, v209
	s_nop 0
	v_cndmask_b32_e32 v93, v224, v93, vcc
	v_cmp_le_i32_e32 vcc, v210, v206
	v_subrev_u32_e32 v210, 37, v209
	s_nop 0
	v_cndmask_b32_e32 v77, v224, v77, vcc
	v_cmp_le_i32_e32 vcc, v210, v206
	v_add_u32_e32 v210, -5, v209
	s_nop 0
	v_cndmask_b32_e32 v94, v224, v94, vcc
	v_cmp_le_i32_e32 vcc, v210, v206
	v_subrev_u32_e32 v210, 36, v209
	v_add_u32_e32 v209, -4, v209
	v_cndmask_b32_e32 v78, v224, v78, vcc
	v_cmp_le_i32_e32 vcc, v210, v206
	s_nop 1
	v_cndmask_b32_e32 v95, v224, v95, vcc
	v_cmp_le_i32_e32 vcc, v209, v206
	s_nop 1
	v_cndmask_b32_e32 v79, v224, v79, vcc

; __device__ __forceinline__ u32x4 pack8(const float (&f)[8]) { u32x4 w; w.x = pk_bf16(f[0], f[1]); w.y = pk_bf16(f[2], f[3]); w.z = pk_bf16(f[4], f[5]); w.w = pk_bf16(f[6], f[7]); return w; }
; __device__ __forceinline__ void attn_phase(LAS unsigned char* lds, const bf16* Q, const bf16* KV, const bf16* KPE, const float* rope, bf16* mix, int bid, int G, int tid) {
;     ...
;                 float mx = fmaxf(S0[0], S1[0]);
; #pragma unroll
;                 for (int e = 1; e < 16; ++e) mx = fmaxf(mx, fmaxf(S0[e], S1[e]));
;                 mx = fmaxf(mx, __shfl_xor(mx, 32));
;                 const float mnew = (mx > mrun + 6.0f) ? mx : mrun;
;                 const float alpha = __builtin_amdgcn_exp2f(mrun - mnew); mrun = mnew;
;                 float rs = 0.f;
; #pragma unroll
;                 for (int e = 0; e < 16; ++e) { S0[e] = __builtin_amdgcn_exp2f(S0[e] - mnew); S1[e] = __builtin_amdgcn_exp2f(S1[e] - mnew); rs += S0[e] + S1[e]; }
;                 lrun = lrun * alpha + rs;
;                 if (__builtin_amdgcn_ballot_w64(alpha != 1.0f) != 0ull) {
; #pragma unroll
;                     for (int i = 0; i < 4; ++i)
; #pragma unroll
;                         for (int e = 0; e < 16; ++e) O[i][e] *= alpha; }
; #pragma unroll
;                 for (int hs = 0; hs < 8; ++hs) { const int st = hs >> 1;
;                     if (hs < 7) { AT_LDV((hs + 1) & 1, hs + 1); }
;                     __builtin_amdgcn_sched_barrier(0);
;                     float pf[8];
; #pragma unroll
;                     for (int e = 0; e < 8; ++e) pf[e] = (st >> 1) ? S1[8 * (st & 1) + e] : S0[8 * (st & 1) + e];
;                     const bf16x8 pb = __builtin_bit_cast(bf16x8, pack8(pf));
; #pragma unroll
;                     for (int d_ = 0; d_ < 2; ++d_) { const int dvt = (hs & 1) * 2 + d_; const s16x4 lo = vf[hs & 1][2 * d_], hi = vf[hs & 1][2 * d_ + 1];
;                         const bf16x8 A = (bf16x8){lo[0], lo[1], lo[2], lo[3], hi[0], hi[1], hi[2], hi[3]};
;                         __builtin_amdgcn_s_setprio(1); O[dvt] = __builtin_amdgcn_mfma_f32_32x32x16_bf16(A, pb, O[dvt], 0, 0, 0); __builtin_amdgcn_s_setprio(0); }
;                     __builtin_amdgcn_sched_barrier(0); }
.LBB0_258:
	v_sub_f32_e32 v80, v80, v209
	v_sub_f32_e32 v64, v64, v209
	v_exp_f32_e32 v80, v80
	v_exp_f32_e32 v210, v64
	v_sub_f32_e32 v81, v81, v209
	v_sub_f32_e32 v65, v65, v209
	v_exp_f32_e32 v81, v81
	v_exp_f32_e32 v211, v65
	v_add_f32_e32 v64, v80, v210
	v_add_f32_e32 v64, 0, v64
	v_add_f32_e32 v65, v81, v211
	v_add_f32_e32 v64, v65, v64
	v_sub_f32_e32 v65, v82, v209
	v_exp_f32_e32 v82, v65
	v_sub_f32_e32 v65, v66, v209
	v_exp_f32_e32 v212, v65
	s_nop 0
	v_add_f32_e32 v65, v82, v212
	v_add_f32_e32 v64, v65, v64
	v_sub_f32_e32 v65, v83, v209
	v_exp_f32_e32 v83, v65
	v_sub_f32_e32 v65, v67, v209
	v_exp_f32_e32 v213, v65
	s_nop 0
	v_add_f32_e32 v65, v83, v213
	v_add_f32_e32 v64, v65, v64
	v_sub_f32_e32 v65, v84, v209
	v_exp_f32_e32 v84, v65
	v_sub_f32_e32 v65, v68, v209
	v_exp_f32_e32 v214, v65
	s_nop 0
	v_add_f32_e32 v65, v84, v214
	v_add_f32_e32 v64, v65, v64
	v_sub_f32_e32 v65, v85, v209
	v_exp_f32_e32 v85, v65
	v_sub_f32_e32 v65, v69, v209
	v_exp_f32_e32 v215, v65
	s_nop 0
	v_add_f32_e32 v65, v85, v215
	v_add_f32_e32 v64, v65, v64
	v_sub_f32_e32 v65, v86, v209
	v_exp_f32_e32 v86, v65
	v_sub_f32_e32 v65, v70, v209
	v_exp_f32_e32 v228, v65
	s_nop 0
	v_add_f32_e32 v65, v86, v228
	v_add_f32_e32 v64, v65, v64
	v_sub_f32_e32 v65, v87, v209
	v_exp_f32_e32 v87, v65
	v_sub_f32_e32 v65, v71, v209
	v_exp_f32_e32 v229, v65
	s_nop 0
	v_add_f32_e32 v65, v87, v229
	v_add_f32_e32 v64, v65, v64
	v_sub_f32_e32 v65, v88, v209
	v_exp_f32_e32 v88, v65
	v_sub_f32_e32 v65, v72, v209
	v_exp_f32_e32 v230, v65
	s_nop 0
	v_add_f32_e32 v65, v88, v230
	v_add_f32_e32 v64, v65, v64
	v_sub_f32_e32 v65, v89, v209
	v_exp_f32_e32 v89, v65
	v_sub_f32_e32 v65, v73, v209
	v_exp_f32_e32 v231, v65
	s_nop 0
	v_add_f32_e32 v65, v89, v231
	v_add_f32_e32 v64, v65, v64
	v_sub_f32_e32 v65, v90, v209
	v_exp_f32_e32 v90, v65
	v_sub_f32_e32 v65, v74, v209
	v_exp_f32_e32 v232, v65
	s_nop 0
	v_add_f32_e32 v65, v90, v232
	v_add_f32_e32 v64, v65, v64
	v_sub_f32_e32 v65, v91, v209
	v_exp_f32_e32 v91, v65
	v_sub_f32_e32 v65, v75, v209
	v_exp_f32_e32 v233, v65
	s_nop 0
	v_add_f32_e32 v65, v91, v233
	v_add_f32_e32 v64, v65, v64
	v_sub_f32_e32 v65, v92, v209
	v_exp_f32_e32 v92, v65
	v_sub_f32_e32 v65, v76, v209
	v_exp_f32_e32 v234, v65
	s_nop 0
	v_add_f32_e32 v65, v92, v234
	v_add_f32_e32 v64, v65, v64
	v_sub_f32_e32 v65, v93, v209
	v_exp_f32_e32 v93, v65
	v_sub_f32_e32 v65, v77, v209
	v_exp_f32_e32 v235, v65
	s_nop 0
	v_add_f32_e32 v65, v93, v235
	v_add_f32_e32 v64, v65, v64
	v_sub_f32_e32 v65, v94, v209
	v_exp_f32_e32 v94, v65
	v_sub_f32_e32 v65, v78, v209
	v_exp_f32_e32 v236, v65
	s_nop 0
	v_add_f32_e32 v65, v94, v236
	v_add_f32_e32 v64, v65, v64
	v_sub_f32_e32 v65, v95, v209
	v_exp_f32_e32 v95, v65
	v_sub_f32_e32 v65, v79, v209
	v_exp_f32_e32 v237, v65
	s_nop 0
	v_add_f32_e32 v65, v95, v237
	v_add_f32_e32 v242, v65, v64
	ds_read_b64_tr_b16 v[64:65], v208 offset:25728
	ds_read_b64_tr_b16 v[66:67], v208 offset:28288
	ds_read_b64_tr_b16 v[68:69], v208 offset:25792
	ds_read_b64_tr_b16 v[70:71], v208 offset:28352
	v_fmac_f32_e32 v242, v207, v184
	v_cvt_pk_bf16_f32 v72, v80, v81
	v_cvt_pk_bf16_f32 v73, v82, v83
	v_cvt_pk_bf16_f32 v74, v84, v85
	v_cvt_pk_bf16_f32 v75, v86, v87
	s_setprio 1
	s_nop 0
	v_mfma_f32_32x32x16_bf16 v[48:63], v[170:173], v[72:75], v[48:63]
	s_setprio 0
	s_setprio 1
	v_mfma_f32_32x32x16_bf16 v[32:47], v[166:169], v[72:75], v[32:47]
	s_setprio 0
	ds_read_b64_tr_b16 v[76:77], v208 offset:30720
	ds_read_b64_tr_b16 v[78:79], v208 offset:33280
	ds_read_b64_tr_b16 v[80:81], v208 offset:30784
	ds_read_b64_tr_b16 v[82:83], v208 offset:33344
	s_setprio 1
	s_waitcnt lgkmcnt(0)
	v_mfma_f32_32x32x16_bf16 v[16:31], v[64:67], v[72:75], v[16:31]
	s_setprio 0
	s_setprio 1
	v_mfma_f32_32x32x16_bf16 v[0:15], v[68:71], v[72:75], v[0:15]
	s_setprio 0
	ds_read_b64_tr_b16 v[64:65], v208 offset:30848
	ds_read_b64_tr_b16 v[66:67], v208 offset:33408
	ds_read_b64_tr_b16 v[68:69], v208 offset:30912
	ds_read_b64_tr_b16 v[70:71], v208 offset:33472
	v_cvt_pk_bf16_f32 v72, v88, v89
	v_cvt_pk_bf16_f32 v73, v90, v91
	v_cvt_pk_bf16_f32 v74, v92, v93
	v_cvt_pk_bf16_f32 v75, v94, v95
	s_setprio 1
	s_nop 0
	v_mfma_f32_32x32x16_bf16 v[48:63], v[76:79], v[72:75], v[48:63]
	s_setprio 0
	s_setprio 1
	v_mfma_f32_32x32x16_bf16 v[32:47], v[80:83], v[72:75], v[32:47]
	s_setprio 0
	ds_read_b64_tr_b16 v[76:77], v208 offset:35840
	ds_read_b64_tr_b16 v[78:79], v208 offset:38400
	ds_read_b64_tr_b16 v[82:83], v208 offset:38464
	ds_read_b64_tr_b16 v[80:81], v208 offset:35904
	s_setprio 1
	s_waitcnt lgkmcnt(0)
	v_mfma_f32_32x32x16_bf16 v[16:31], v[64:67], v[72:75], v[16:31]
	s_setprio 0
	s_setprio 1
	v_mfma_f32_32x32x16_bf16 v[0:15], v[68:71], v[72:75], v[0:15]
	s_setprio 0
	ds_read_b64_tr_b16 v[64:65], v208 offset:35968
	ds_read_b64_tr_b16 v[66:67], v208 offset:38528
	ds_read_b64_tr_b16 v[70:71], v208 offset:38592
	ds_read_b64_tr_b16 v[68:69], v208 offset:36032
	v_cvt_pk_bf16_f32 v72, v210, v211
	v_cvt_pk_bf16_f32 v73, v212, v213
	v_cvt_pk_bf16_f32 v74, v214, v215
	v_cvt_pk_bf16_f32 v75, v228, v229
	s_setprio 1
	s_nop 0
	v_mfma_f32_32x32x16_bf16 v[48:63], v[76:79], v[72:75], v[48:63]
	s_setprio 0
	s_setprio 1
	v_mfma_f32_32x32x16_bf16 v[32:47], v[80:83], v[72:75], v[32:47]
	s_setprio 0
	ds_read_b64_tr_b16 v[76:77], v208 offset:40960
	ds_read_b64_tr_b16 v[78:79], v208 offset:43520
	ds_read_b64_tr_b16 v[82:83], v208 offset:43584
	ds_read_b64_tr_b16 v[80:81], v208 offset:41024
	s_setprio 1
	s_waitcnt lgkmcnt(0)
	v_mfma_f32_32x32x16_bf16 v[16:31], v[64:67], v[72:75], v[16:31]
	s_setprio 0
	s_setprio 1
	v_mfma_f32_32x32x16_bf16 v[0:15], v[68:71], v[72:75], v[0:15]
	s_setprio 0
	ds_read_b64_tr_b16 v[64:65], v208 offset:41088
	ds_read_b64_tr_b16 v[66:67], v208 offset:43648
	ds_read_b64_tr_b16 v[70:71], v208 offset:43712
	ds_read_b64_tr_b16 v[68:69], v208 offset:41152
	v_cvt_pk_bf16_f32 v72, v230, v231
	v_cvt_pk_bf16_f32 v73, v232, v233
	v_cvt_pk_bf16_f32 v74, v234, v235
	v_cvt_pk_bf16_f32 v75, v236, v237
	s_setprio 1
	s_nop 0
	v_mfma_f32_32x32x16_bf16 v[48:63], v[76:79], v[72:75], v[48:63]
	s_setprio 0
	s_setprio 1
	v_mfma_f32_32x32x16_bf16 v[32:47], v[80:83], v[72:75], v[32:47]
	s_setprio 0
	s_setprio 1
	s_waitcnt lgkmcnt(0)
	v_mfma_f32_32x32x16_bf16 v[16:31], v[64:67], v[72:75], v[16:31]
	s_setprio 0
	s_setprio 1
	v_mfma_f32_32x32x16_bf16 v[0:15], v[68:71], v[72:75], v[0:15]
	s_setprio 0
	v_mov_b32_e32 v207, v242
	s_branch .LBB0_260
.LBB0_259:
	v_mov_b32_e32 v209, v184
	s_cmp_eq_u32 s17, 0
	s_cbranch_scc1 .LBB0_260
	s_andn2_b64 vcc, exec, s[34:35]
	s_cbranch_vccnz .Latt_xnc_b
	s_bitcmp1_b32 s1, 0
	s_cselect_b32 s4, 0x6400, 0
	s_add_i32 s15, s14, 0x5000
	s_cmp_gt_u32 s15, 0x10400
	s_cselect_b32 s15, 0x6400, s15
	v_add3_u32 v250, s4, v190, v187
	s_waitcnt vmcnt(0) lgkmcnt(0)
	ds_write_b128 v250, v[138:141]
	v_add3_u32 v250, s4, v191, v187
	ds_write_b128 v250, v[142:145]
	v_add3_u32 v250, s4, v192, v188
	ds_write_b128 v250, v[150:153] offset:256
	v_add3_u32 v250, s15, v193, v187
	ds_write_b128 v250, v[146:149] offset:25600
	v_add3_u32 v250, s15, v202, v187
	ds_write_b128 v250, v[154:157] offset:25600

; __device__ __forceinline__ void attn_phase(LAS unsigned char* lds, const bf16* Q, const bf16* KV, const bf16* KPE, const float* rope, bf16* mix, int bid, int G, int tid) {
;     ...
;             if (kt + 1 < ntiles) AT_COMMIT(lds + ((kt + 1) & 1) * AT_BUF);
;             __syncthreads();
;         }
.Latt_xni_b:
.LBB0_260:
	s_cmp_lg_u32 s17, 0
	s_cbranch_scc1 .LBB0_261
	s_andn2_b64 vcc, exec, s[34:35]
	s_cbranch_vccnz .LBB0_261
	s_bitcmp1_b32 s1, 0
	s_cselect_b32 s4, 0x6400, 0
	s_add_i32 s15, s14, 0x5000
	s_cmp_gt_u32 s15, 0x10400
	s_cselect_b32 s15, 0x6400, s15
	v_add3_u32 v64, s4, v190, v187
	s_waitcnt vmcnt(0) lgkmcnt(0)
	ds_write_b128 v64, v[138:141]
	v_add3_u32 v64, s4, v191, v187
	ds_write_b128 v64, v[142:145]
	v_add3_u32 v64, s4, v192, v188
	ds_write_b128 v64, v[150:153] offset:256
	v_add3_u32 v64, s15, v193, v187
	ds_write_b128 v64, v[146:149] offset:25600
	v_add3_u32 v64, s15, v202, v187
	ds_write_b128 v64, v[154:157] offset:25600
.LBB0_261:
	s_mov_b64 s[4:5], 0x2000
	s_add_i32 s0, s0, 64
	v_lshl_add_u64 v[176:177], v[176:177], 0, s[4:5]
	s_mov_b64 s[4:5], 0x60000
	v_lshl_add_u64 v[178:179], v[178:179], 0, s[4:5]
	v_lshl_add_u64 v[180:181], v[180:181], 0, s[4:5]
	v_lshl_add_u64 v[182:183], v[182:183], 0, s[4:5]
	s_add_i32 s14, s14, 0x5000
	s_cmp_gt_u32 s14, 0x10400
	s_cselect_b32 s14, 0x6400, s14
	s_cmp_lg_u32 s17, 0
	s_cbranch_scc1 .Latt_nobar
	s_waitcnt lgkmcnt(0)
	s_barrier
.Latt_nobar:
	s_cmp_eq_u32 s9, s1
	s_cbranch_scc1 .Latt_exit
	v_mov_b32_e32 v184, v209
	s_mov_b32 s4, s1
	s_branch .LBB0_251
.Latt_exit:
	s_waitcnt lgkmcnt(0)
	s_barrier
	s_branch .LBB0_239
